# MLA inner loop hand-rescheduled: persistent -m SrcC block (no per-tile S init movs), lazy softmax rescale (threshold 2^8), next-tile LDS stores hoisted after previous barrier, Vt tile-major layout, ph
# speedup vs baseline: 1.0311x; 1.0311x over previous
; DI int tid() { int t = threadIdx.x; asm volatile("" : "+v"(t)); return t; }
; DI int crow(int r, int h) { return (r & 3) + 8 * (r >> 2) + 4 * h; }
; DI void ph_up(KP p, int l, char* smem) {
;     ...
;         const int tt = tid(), lane = tt & 63, w = __builtin_amdgcn_readfirstlane(tt >> 6), wm = w >> 1, wn = w & 1, l32 = lane & 31, h = lane >> 5;
; #pragma unroll
;         for (int i = 0; i < 2; ++i)
; #pragma unroll
;             for (int j = 0; j < 2; ++j)
; #pragma unroll
;                 for (int r = 0; r < 16; ++r) {
;                     const int row = wm * 64 + i * 32 + crow(r, h), col = wn * 64 + j * 32 + l32;
;                     stg[row * 130 + col] = acc[i][j][r] * rs[row];
;                 }
;         __syncthreads();
;         bf16_t* act = (bf16_t*)(p->ws + OFF_ACT);
;         const int rmax = min(126, SEQ - s0);
;         const int rbeg = w * 32 + h * 16, rend = min(rbeg + 16, rmax);
;         if (rbeg < rend) {
;             const float* sg = stg + rbeg * 130 + cp2;
;             unsigned* arow = (unsigned*)(act + ((size_t)b * SEQ + s0 + rbeg) * DFF + c);
.LBB0_79:
	s_or_b64 exec, exec, s[16:17]
	v_mov_b32_e32 v34, v182
	s_waitcnt lgkmcnt(0)
	s_barrier
	s_nop 0
	v_readfirstlane_b32 s12, v34
	s_ashr_i32 s11, s12, 1
	v_bfe_u32 v68, v34, 5, 1
	s_and_b32 s13, s11, 0xffffffc0
	v_lshl_or_b32 v69, v68, 2, s13
	v_lshl_add_u32 v70, v69, 2, 0
	v_add_u32_e32 v70, 0x12000, v70
	ds_read_b128 v[198:201], v70
	ds_read_b128 v[202:205], v70 offset:32
	ds_read_b128 v[206:209], v70 offset:64
	ds_read_b128 v[210:213], v70 offset:96
	v_and_b32_e32 v34, 31, v34
	v_and_or_b32 v34, s12, 64, v34
	s_movk_i32 s12, 0x208
	v_mul_lo_u32 v69, v69, s12
	v_lshlrev_b32_e32 v34, 2, v34
	v_add3_u32 v34, 0, v69, v34
	s_andn2_b32 s11, s11, 31
	s_sub_i32 s12, 0x2000, s10
	s_waitcnt lgkmcnt(0)
	v_mul_f32_e32 v52, v52, v198
	v_mul_f32_e32 v53, v53, v199
	v_mul_f32_e32 v54, v54, v200
	v_mul_f32_e32 v55, v55, v201
	v_mul_f32_e32 v56, v56, v202
	v_mul_f32_e32 v57, v57, v203
	v_mul_f32_e32 v58, v58, v204
	v_mul_f32_e32 v59, v59, v205
	v_mul_f32_e32 v60, v60, v206
	v_mul_f32_e32 v61, v61, v207
	v_mul_f32_e32 v62, v62, v208
	v_mul_f32_e32 v63, v63, v209
	v_mul_f32_e32 v64, v64, v210
	v_mul_f32_e32 v65, v65, v211
	v_mul_f32_e32 v66, v66, v212
	v_mul_f32_e32 v67, v67, v213
	v_mul_f32_e32 v36, v36, v198
	v_mul_f32_e32 v37, v37, v199
	v_mul_f32_e32 v38, v38, v200
	v_mul_f32_e32 v39, v39, v201
	v_mul_f32_e32 v40, v40, v202
	v_mul_f32_e32 v41, v41, v203
	v_mul_f32_e32 v42, v42, v204
	v_mul_f32_e32 v43, v43, v205
	v_mul_f32_e32 v44, v44, v206
	v_mul_f32_e32 v45, v45, v207
	v_mul_f32_e32 v46, v46, v208
	v_mul_f32_e32 v47, v47, v209
	v_mul_f32_e32 v48, v48, v210
	v_mul_f32_e32 v49, v49, v211
	v_mul_f32_e32 v50, v50, v212
	v_mul_f32_e32 v51, v51, v213
	ds_read_b128 v[198:201], v70 offset:128
	ds_read_b128 v[202:205], v70 offset:160
	ds_read_b128 v[206:209], v70 offset:192
	ds_read_b128 v[210:213], v70 offset:224
	ds_write_b32 v34, v52
	ds_write_b32 v34, v53 offset:520
	ds_write_b32 v34, v54 offset:1040
	ds_write_b32 v34, v55 offset:1560
	ds_write_b32 v34, v56 offset:4160
	ds_write_b32 v34, v57 offset:4680
	ds_write_b32 v34, v58 offset:5200
	ds_write_b32 v34, v59 offset:5720
	ds_write_b32 v34, v60 offset:8320
	ds_write_b32 v34, v61 offset:8840
	ds_write_b32 v34, v62 offset:9360
	ds_write_b32 v34, v63 offset:9880
	ds_write_b32 v34, v64 offset:12480
	ds_write_b32 v34, v65 offset:13000
	ds_write_b32 v34, v66 offset:13520
	ds_write_b32 v34, v67 offset:14040
	ds_write_b32 v34, v36 offset:128
	ds_write_b32 v34, v37 offset:648
	ds_write_b32 v34, v38 offset:1168
	ds_write_b32 v34, v39 offset:1688
	ds_write_b32 v34, v40 offset:4288
	ds_write_b32 v34, v41 offset:4808
	ds_write_b32 v34, v42 offset:5328
	ds_write_b32 v34, v43 offset:5848
	ds_write_b32 v34, v44 offset:8448
	ds_write_b32 v34, v45 offset:8968
	ds_write_b32 v34, v46 offset:9488
	ds_write_b32 v34, v47 offset:10008
	ds_write_b32 v34, v48 offset:12608
	ds_write_b32 v34, v49 offset:13128
	ds_write_b32 v34, v50 offset:13648
	ds_write_b32 v34, v51 offset:14168
	s_waitcnt lgkmcnt(0)
	v_mul_f32_e32 v16, v16, v198
	v_mul_f32_e32 v17, v17, v199
	v_mul_f32_e32 v18, v18, v200
	v_mul_f32_e32 v19, v19, v201
	v_mul_f32_e32 v20, v20, v202
	v_mul_f32_e32 v21, v21, v203
	v_mul_f32_e32 v22, v22, v204
	v_mul_f32_e32 v23, v23, v205
	v_mul_f32_e32 v24, v24, v206
	v_mul_f32_e32 v25, v25, v207
	v_mul_f32_e32 v26, v26, v208
	v_mul_f32_e32 v27, v27, v209
	v_mul_f32_e32 v28, v28, v210
	v_mul_f32_e32 v29, v29, v211
	v_mul_f32_e32 v30, v30, v212
	v_mul_f32_e32 v31, v31, v213
	v_mul_f32_e32 v0, v0, v198
	v_mul_f32_e32 v1, v1, v199
	v_mul_f32_e32 v2, v2, v200
	v_mul_f32_e32 v3, v3, v201
	v_mul_f32_e32 v4, v4, v202
	v_mul_f32_e32 v5, v5, v203
	v_mul_f32_e32 v6, v6, v204
	v_mul_f32_e32 v7, v7, v205
	v_mul_f32_e32 v8, v8, v206
	v_mul_f32_e32 v9, v9, v207
	v_mul_f32_e32 v10, v10, v208
	v_mul_f32_e32 v11, v11, v209
	v_mul_f32_e32 v12, v12, v210
	v_mul_f32_e32 v13, v13, v211
	v_mul_f32_e32 v14, v14, v212
	v_mul_f32_e32 v15, v15, v213
	ds_write_b32 v34, v16 offset:16640
	ds_write_b32 v34, v17 offset:17160
	ds_write_b32 v34, v18 offset:17680
	ds_write_b32 v34, v19 offset:18200
	ds_write_b32 v34, v20 offset:20800
	ds_write_b32 v34, v21 offset:21320
	ds_write_b32 v34, v22 offset:21840
	ds_write_b32 v34, v23 offset:22360
	ds_write_b32 v34, v24 offset:24960
	ds_write_b32 v34, v25 offset:25480
	ds_write_b32 v34, v26 offset:26000
	ds_write_b32 v34, v27 offset:26520
	ds_write_b32 v34, v28 offset:29120
	ds_write_b32 v34, v29 offset:29640
	ds_write_b32 v34, v30 offset:30160
	ds_write_b32 v34, v31 offset:30680
	ds_write_b32 v34, v0 offset:16768
	ds_write_b32 v34, v1 offset:17288
	ds_write_b32 v34, v2 offset:17808
	ds_write_b32 v34, v3 offset:18328
	ds_write_b32 v34, v4 offset:20928
	ds_write_b32 v34, v5 offset:21448
	ds_write_b32 v34, v6 offset:21968
	ds_write_b32 v34, v7 offset:22488
	ds_write_b32 v34, v8 offset:25088
	ds_write_b32 v34, v9 offset:25608
	ds_write_b32 v34, v10 offset:26128
	ds_write_b32 v34, v11 offset:26648
	ds_write_b32 v34, v12 offset:29248
	ds_write_b32 v34, v13 offset:29768
	ds_write_b32 v34, v14 offset:30288
	ds_write_b32 v34, v15 offset:30808
	v_lshlrev_b32_e32 v16, 4, v68
	v_or_b32_e32 v8, s11, v16
	v_add_u32_e32 v12, 16, v8
	v_min3_i32 v14, s12, v12, v193
	v_cmp_lt_i32_e32 vcc, v8, v14
	s_waitcnt lgkmcnt(0)
	s_barrier
	s_and_saveexec_b64 s[16:17], vcc
	s_cbranch_execz .LBB0_57
	s_load_dwordx2 s[12:13], s[0:1], 0xe0
	s_movk_i32 s15, 0x208
	v_mul_lo_u32 v0, v8, s15
	s_ashr_i32 s15, s14, 31
	s_lshl_b64 s[18:19], s[14:15], 13
	s_ashr_i32 s15, s10, 31
	s_add_u32 s18, s18, s10
	v_lshlrev_b32_e32 v1, 2, v164
	s_addc_u32 s19, s19, s15
	v_ashrrev_i32_e32 v9, 31, v8
	v_add3_u32 v15, 0, v0, v1
	v_lshl_add_u64 v[0:1], s[18:19], 0, v[8:9]
	s_waitcnt lgkmcnt(0)
	v_mov_b64_e32 v[2:3], s[12:13]
	s_movk_i32 s10, 0x1600
	v_mad_u64_u32 v[2:3], s[12:13], v0, s10, v[2:3]
	v_mad_i32_i24 v3, v1, s10, v3
	v_lshl_add_u64 v[0:1], v[146:147], 1, v[2:3]
	s_mov_b64 s[12:13], 0xa180000
	v_lshl_add_u64 v[10:11], v[0:1], 0, s[12:13]
	ds_read2_b64 v[0:3], v15 offset1:32
	ds_read2_b64 v[4:7], v15 offset0:65 offset1:97
	v_and_b32_e32 v13, 2, v14
	v_cmp_ne_u32_e32 vcc, 0, v13
	s_and_saveexec_b64 s[18:19], vcc
	s_cbranch_execz .LBB0_84
	s_and_b32 s10, s7, 7
	s_add_i32 s9, s9, s10
	s_mul_i32 s10, s14, 0x42
	s_sub_i32 s9, s9, s10
	s_mulk_i32 s9, 0x7e
	s_sub_i32 s9, 0x2000, s9
	v_min3_i32 v8, v12, s9, v193
	v_bfe_u32 v8, v8, 1, 1
	v_mul_u32_u24_e32 v9, 0x410, v8
	v_add3_u32 v8, s11, v16, v13
	s_mov_b32 s9, 0
	s_mov_b64 s[14:15], 0
	s_waitcnt vmcnt(0)

; DI int tid() { int t = threadIdx.x; asm volatile("" : "+v"(t)); return t; }
; #define M2_STORE(S, buf) { M2_SK(0, S##k0, buf) M2_SK(1, S##k1, buf) M2_SK(2, S##k2, buf) M2_SV(0, S##v0, buf) M2_SV(1, S##v1, buf) }
; DI void flash_mla2(const bf16_t* __restrict__ Qp, const bf16_t* __restrict__ Kp, const bf16_t* __restrict__ Vtp,
;                    bf16_t* __restrict__ Op, char* smem, float& ssq) {
;     ...
;     const int t = tid(), lane = t & 63, w = __builtin_amdgcn_readfirstlane(t >> 6), l32 = lane & 31, h = lane >> 5;
;     const int q = w * 32 + l32;
;     const unsigned ktoff = (unsigned)(t * 8);
;     const unsigned vtoff = (unsigned)((t >> 3) * LDV + (t & 7) * 8);
;     bf16x8 qf[NKS];
; #pragma unroll
;     for (int ks = 0; ks < NKS; ++ks) qf[ks] = *(const bf16x8*)(Qp + (size_t)q * LDQ + ks * 16 + 8 * h);
;     f32x16 o[NMT];
; #pragma unroll
;     for (int mt = 0; mt < NMT; ++mt)
; #pragma unroll
;         for (int r = 0; r < 16; ++r) o[mt][r] = 0.f;
;     float m = 0.f, lsum = 0.f;
;     uint4 ak0, ak1, ak2, av0, av1, bk0, bk1, bk2, bv0, bv1;
;     ...
;     float alpha = 1.f;
;     __syncthreads();
;     M2_LOAD(a, 0);
;     M2_LOAD(b, 1);
;     {
;         M2_STORE(a, 0);
;         __syncthreads();
.LBB0_182:
	s_add_i32 s18, s34, s13
	s_ashr_i32 s19, s18, 31
	s_lshl_b64 s[16:17], s[18:19], 13
	s_or_b32 s16, s16, s12
	s_mulk_i32 s17, 0xc0
	s_mul_hi_u32 s35, s16, 0xc0
	s_add_i32 s35, s35, s17
	s_mulk_i32 s16, 0xc0
	s_add_u32 s36, s6, s16
	s_addc_u32 s37, s7, s35
	s_mul_i32 s16, s18, 0x180000
	s_mul_hi_i32 s17, s18, 0x180000
	s_add_u32 s16, s8, s16
	s_addc_u32 s17, s9, s17
	s_lshl_b64 s[18:19], s[18:19], 20
	v_mov_b32_e32 v1, v182
	s_add_u32 s18, s10, s18
	s_addc_u32 s19, s11, s19
	v_readfirstlane_b32 s35, v1
	s_ashr_i32 s35, s35, 1
	s_waitcnt vmcnt(1)
	v_bfe_u32 v142, v1, 5, 1
	v_mov_b32_e32 v2, s35
	v_bfi_b32 v132, s80, v2, v1
	v_mov_b64_e32 v[2:3], s[36:37]
	v_mad_i64_i32 v[2:3], s[36:37], v132, s86, v[2:3]
	v_lshlrev_b32_e32 v4, 4, v142
	v_mov_b32_e32 v5, v35
	v_lshlrev_b32_e32 v34, 3, v1
	v_lshl_add_u64 v[2:3], v[2:3], 0, v[4:5]
	global_load_dwordx4 v[68:71], v[2:3], off
	global_load_dwordx4 v[72:75], v[2:3], off offset:32
	global_load_dwordx4 v[76:79], v[2:3], off offset:64
	global_load_dwordx4 v[80:83], v[2:3], off offset:96
	global_load_dwordx4 v[84:87], v[2:3], off offset:128
	global_load_dwordx4 v[88:91], v[2:3], off offset:160
	v_lshl_add_u64 v[2:3], v[34:35], 1, s[16:17]
	v_add_co_u32_e32 v6, vcc, s84, v2
	v_ashrrev_i32_e32 v5, 3, v1
	v_and_b32_e32 v12, 56, v34
	v_addc_co_u32_e32 v7, vcc, 0, v3, vcc
	v_lshl_or_b32 v134, v5, 6, v12
	v_mov_b32_e32 v135, v35
	s_barrier
	global_load_dwordx4 v[92:95], v[2:3], off
	global_load_dwordx4 v[100:103], v[6:7], off offset:-4096
	global_load_dwordx4 v[96:99], v[6:7], off
	v_lshl_add_u64 v[6:7], v[134:135], 1, s[18:19]
	s_mov_b32 s35, 0x1000
	v_add_co_u32_e32 v8, vcc, s35, v6
	global_load_dwordx4 v[104:107], v[6:7], off
	s_nop 0
	v_addc_co_u32_e32 v9, vcc, 0, v7, vcc
	global_load_dwordx4 v[108:111], v[8:9], off
	v_mul_hi_i32 v10, v1, s87
	v_add_u32_e32 v13, 0x100, v1
	v_lshrrev_b32_e32 v11, 31, v10
	v_ashrrev_i32_e32 v10, 1, v10
	v_mul_hi_i32 v14, v13, s87
	v_add_u32_e32 v10, v10, v11
	v_lshrrev_b32_e32 v11, 31, v14
	v_ashrrev_i32_e32 v14, 1, v14
	v_mul_lo_u32 v15, v10, -12
	v_and_b32_e32 v16, 0xffffff3, v10
	v_lshlrev_b32_e32 v17, 1, v10
	v_lshrrev_b32_e32 v10, 1, v10
	v_add_u32_e32 v14, v14, v11
	v_and_b32_e32 v11, 8, v17
	v_and_b32_e32 v10, 4, v10
	v_or3_b32 v10, v11, v16, v10
	v_add_lshl_u32 v15, v15, v1, 4
	v_mul_lo_u32 v10, v10, s88
	s_movk_i32 s35, 0x4000
	s_waitcnt vmcnt(11)
	v_add3_u32 v144, 0, v10, v15
	v_add_co_u32_e32 v10, vcc, s35, v2
	v_lshlrev_b32_e32 v19, 1, v14
	s_nop 0
	v_addc_co_u32_e32 v11, vcc, 0, v3, vcc
	v_add_co_u32_e32 v2, vcc, s83, v2
	v_and_b32_e32 v18, 0xffffff3, v14
	s_nop 0
	v_addc_co_u32_e32 v3, vcc, 0, v3, vcc
	v_add_co_u32_e32 v6, vcc, 0x2000, v6
	s_nop 1
	v_addc_co_u32_e32 v7, vcc, 0, v7, vcc
	v_add_co_u32_e32 v8, vcc, 0x2000, v8
	s_nop 1
	v_addc_co_u32_e32 v9, vcc, 0, v9, vcc
	global_load_dwordx4 v[112:115], v[10:11], off offset:-4096
	global_load_dwordx4 v[116:119], v[10:11], off
	global_load_dwordx4 v[120:123], v[6:7], off
	global_load_dwordx4 v[124:127], v[2:3], off
	global_load_dwordx4 v[128:131], v[8:9], off
	v_lshrrev_b32_e32 v2, 1, v14
	v_and_b32_e32 v16, 8, v19
	v_and_b32_e32 v2, 4, v2
	v_mul_lo_u32 v17, v14, -12
	v_or3_b32 v2, v16, v18, v2
	v_and_b32_e32 v44, 31, v1
	v_mul_lo_u32 v2, v2, s88
	v_add_lshl_u32 v3, v17, v13, 4
	v_add_u32_e32 v1, 0x200, v1
	v_add3_u32 v145, 0, v2, v3
	v_mul_hi_i32 v2, v1, s87
	v_lshrrev_b32_e32 v3, 31, v2
	v_ashrrev_i32_e32 v2, 1, v2
	v_add_u32_e32 v2, v2, v3
	v_mul_lo_u32 v3, v2, -12
	v_and_b32_e32 v6, 0xffffff3, v2
	v_lshlrev_b32_e32 v7, 1, v2
	v_lshrrev_b32_e32 v2, 1, v2
	v_and_b32_e32 v7, 8, v7
	v_and_b32_e32 v2, 4, v2
	v_or3_b32 v2, v7, v6, v2
	v_mul_lo_u32 v2, v2, s88
	v_add_lshl_u32 v1, v3, v1, 4
	v_add3_u32 v146, 0, v2, v1
	v_mul_lo_u32 v1, v5, s81
	v_lshlrev_b32_e32 v2, 1, v12
	v_add3_u32 v147, 0, v1, v2
	v_lshrrev_b32_e32 v1, 3, v13
	v_mul_lo_u32 v1, v1, s81
	v_add3_u32 v148, 0, v1, v2
	v_mul_u32_u24_e32 v1, 0x68, v44
	v_lshlrev_b32_e32 v1, 1, v1
	v_add3_u32 v149, 0, v1, v4
	v_ashrrev_i32_e32 v133, 31, v132
	v_mov_b32_e32 v138, 1.0
	s_mov_b32 s35, -2
	v_mov_b32_e32 v140, 0
	s_waitcnt vmcnt(9)
	ds_write_b128 v144, v[92:95]
	s_waitcnt vmcnt(8)
	ds_write_b128 v145, v[100:103]
	s_waitcnt vmcnt(7)
	ds_write_b128 v146, v[96:99]
	s_waitcnt vmcnt(6)
	ds_write_b128 v147, v[104:107] offset:26624
	s_waitcnt vmcnt(5)
	ds_write_b128 v148, v[108:111] offset:26624
	s_add_u32 s36, s16, 0x6000
	s_addc_u32 s37, s17, 0
	s_mov_b32 s41, 2
	v_lshl_add_u64 v[36:37], v[34:35], 1, s[36:37]
	s_lshl_b32 s36, s41, 13
	global_load_dwordx4 v[92:95], v[36:37], off
	v_add_co_u32_e32 v36, vcc, s84, v36
	s_add_u32 s36, s18, s36
	s_nop 0
	v_addc_co_u32_e32 v37, vcc, 0, v37, vcc
	s_addc_u32 s37, s19, 0
	global_load_dwordx4 v[100:103], v[36:37], off offset:-4096
	global_load_dwordx4 v[96:99], v[36:37], off
	v_lshl_add_u64 v[36:37], v[134:135], 1, s[36:37]
	global_load_dwordx4 v[104:107], v[36:37], off
	v_add_co_u32_e32 v36, vcc, 0x1000, v36
	s_nop 1
	v_addc_co_u32_e32 v37, vcc, 0, v37, vcc
	global_load_dwordx4 v[108:111], v[36:37], off
	s_waitcnt lgkmcnt(0)
	s_barrier
; #define MFMA(a, b, c) __builtin_amdgcn_mfma_f32_32x32x16_bf16((a), (b), (c), 0, 0, 0)
; #define M2_STORE(S, buf) { M2_SK(0, S##k0, buf) M2_SK(1, S##k1, buf) M2_SK(2, S##k2, buf) M2_SV(0, S##v0, buf) M2_SV(1, S##v1, buf) }
; DI void flash_mla2(const bf16_t* __restrict__ Qp, const bf16_t* __restrict__ Kp, const bf16_t* __restrict__ Vtp,
;                    bf16_t* __restrict__ Op, char* smem, float& ssq) {
;     ...
;         const bf16_t* kb = Ks + l32 * KP + 8 * h;
;         f32x16 s0, s1;
; #pragma unroll
;         for (int r = 0; r < 16; ++r) { s0[r] = 0.f; s1[r] = 0.f; }
; #pragma unroll
;         for (int ks = 0; ks < NKS; ++ks) { bf16x8 k0 = *(const bf16x8*)(kb + ks * 16); bf16x8 k1 = *(const bf16x8*)(kb + 32 * KP + ks * 16); s0 = MFMA(k0, qf[ks], s0); s1 = MFMA(k1, qf[ks], s1); }
;         float mx = s0[0];
; #pragma unroll
;         for (int r = 1; r < 16; ++r) mx = fmaxf(mx, s0[r]);
; #pragma unroll
;         for (int r = 0; r < 16; ++r) mx = fmaxf(mx, s1[r]);
;         m = fmaxf(mx, __shfl_xor(mx, 32));
;         __syncthreads();
;     }
;     for (int kt = 0; kt < NKT; kt += 2) {
;         M2_STORE(a, 0);
;         __syncthreads();
;         M2_LOAD(a, min(kt + 2, NKT - 1));
;         M2_COMPUTE(0);
;         M2_STORE(b, 1);
;         __syncthreads();
;         M2_LOAD(b, min(kt + 3, NKT - 1));
	ds_read_b128 v[2:5], v149
	ds_read_b128 v[18:21], v149 offset:32
	s_waitcnt lgkmcnt(1)
	v_mfma_f32_32x32x16_bf16 v[2:17], v[2:5], v[68:71], 0
	s_waitcnt lgkmcnt(0)
	v_mfma_f32_32x32x16_bf16 v[2:17], v[18:21], v[72:75], v[2:17]
	ds_read_b128 v[18:21], v149 offset:64
	ds_read_b128 v[22:25], v149 offset:96
	s_waitcnt lgkmcnt(1)
	v_mfma_f32_32x32x16_bf16 v[2:17], v[18:21], v[76:79], v[2:17]
	s_waitcnt lgkmcnt(0)
	v_mfma_f32_32x32x16_bf16 v[2:17], v[22:25], v[80:83], v[2:17]
	ds_read_b128 v[18:21], v149 offset:128
	ds_read_b128 v[22:25], v149 offset:160
	s_waitcnt lgkmcnt(1)
	v_mfma_f32_32x32x16_bf16 v[2:17], v[18:21], v[84:87], v[2:17]
	ds_read_b128 v[18:21], v149 offset:6656
	ds_read_b128 v[36:39], v149 offset:6688
	s_waitcnt lgkmcnt(2)
	v_mfma_f32_32x32x16_bf16 v[2:17], v[22:25], v[88:91], v[2:17]
	s_waitcnt lgkmcnt(1)
	v_mfma_f32_32x32x16_bf16 v[18:33], v[18:21], v[68:71], 0
	s_nop 9
	v_max_f32_e32 v1, v3, v3
	v_max_f32_e32 v2, v2, v2
	v_max_f32_e32 v1, v2, v1
	v_max3_f32 v1, v1, v4, v5
	v_max3_f32 v1, v1, v6, v7
	v_max3_f32 v1, v1, v8, v9
	v_max3_f32 v1, v1, v10, v11
	s_waitcnt lgkmcnt(0)
	v_mfma_f32_32x32x16_bf16 v[18:33], v[36:39], v[72:75], v[18:33]
	ds_read_b128 v[36:39], v149 offset:6720
	ds_read_b128 v[40:43], v149 offset:6752
	v_max3_f32 v1, v1, v12, v13
	v_max3_f32 v1, v1, v14, v15
	v_max3_f32 v1, v1, v16, v17
	v_xor_b32_e32 v2, 32, v184
	v_cmp_lt_i32_e32 vcc, v2, v187
	v_mov_b32_e32 v3, v0
	s_waitcnt lgkmcnt(1)
	v_mfma_f32_32x32x16_bf16 v[18:33], v[36:39], v[76:79], v[18:33]
	v_cndmask_b32_e32 v2, v184, v2, vcc
	v_lshlrev_b32_e32 v143, 2, v2
	v_mov_b32_e32 v4, v0
	v_mov_b32_e32 v5, v0
	v_mov_b32_e32 v6, v0
	v_mov_b32_e32 v7, v0
	v_mov_b32_e32 v8, v0
	s_waitcnt lgkmcnt(0)
	v_mfma_f32_32x32x16_bf16 v[18:33], v[40:43], v[80:83], v[18:33]
	ds_read_b128 v[36:39], v149 offset:6784
	ds_read_b128 v[40:43], v149 offset:6816
	v_mov_b32_e32 v9, v0
	v_mov_b32_e32 v10, v0
	v_mov_b32_e32 v11, v0
	v_mov_b32_e32 v12, v0
	v_mov_b32_e32 v13, v0
	v_mov_b32_e32 v14, v0
	s_waitcnt lgkmcnt(1)
	v_mfma_f32_32x32x16_bf16 v[18:33], v[36:39], v[84:87], v[18:33]
	v_mov_b32_e32 v15, v0
	v_mov_b32_e32 v16, v0
	v_mov_b32_e32 v17, v0
	s_waitcnt lgkmcnt(0)
	s_barrier
	v_mfma_f32_32x32x16_bf16 v[18:33], v[40:43], v[88:91], v[18:33]
	s_nop 11
	v_max3_f32 v1, v1, v18, v19
	v_max3_f32 v1, v1, v20, v21
	v_max3_f32 v1, v1, v22, v23
	v_max3_f32 v1, v1, v24, v25
	v_max3_f32 v1, v1, v26, v27
	v_max3_f32 v1, v1, v28, v29
	v_max3_f32 v1, v1, v30, v31
	v_max3_f32 v1, v1, v32, v33
	ds_bpermute_b32 v2, v143, v1
	v_mov_b32_e32 v18, v0
	v_mov_b32_e32 v19, v0
	v_mov_b32_e32 v20, v0
	v_mov_b32_e32 v21, v0
	s_waitcnt lgkmcnt(0)
	v_max_f32_e32 v2, v2, v2
	v_max_f32_e32 v141, v1, v2
	v_lshlrev_b32_e32 v1, 6, v44
	v_mov_b32_e32 v2, v0
	v_mov_b32_e32 v22, v0
	v_mov_b32_e32 v23, v0
	v_mov_b32_e32 v24, v0
	v_mov_b32_e32 v25, v0
	v_mov_b32_e32 v26, v0
	v_mov_b32_e32 v27, v0
	v_mov_b32_e32 v28, v0
	v_mov_b32_e32 v29, v0
	v_mov_b32_e32 v30, v0
	v_mov_b32_e32 v31, v0
	v_sub_u32_e32 v150, v149, v1
	v_mov_b32_e32 v1, v0
	v_mov_b64_e32 v[32:33], v[30:31]
	v_mov_b64_e32 v[30:31], v[28:29]
	v_mov_b64_e32 v[28:29], v[26:27]
	v_mov_b64_e32 v[26:27], v[24:25]
	v_mov_b64_e32 v[24:25], v[22:23]
	v_mov_b64_e32 v[22:23], v[20:21]
	v_mov_b64_e32 v[20:21], v[18:19]
	v_mov_b64_e32 v[18:19], v[16:17]
	v_mov_b64_e32 v[16:17], v[14:15]
	v_mov_b64_e32 v[14:15], v[12:13]
	v_mov_b64_e32 v[12:13], v[10:11]
	v_mov_b64_e32 v[10:11], v[8:9]
	v_mov_b64_e32 v[8:9], v[6:7]
	v_mov_b64_e32 v[6:7], v[4:5]
	v_mov_b64_e32 v[4:5], v[2:3]
	v_mov_b64_e32 v[2:3], v[0:1]
	v_xor_b32_e32 v179, 0x80000000, v141
	v_mov_b32_e32 v232, v179
	v_mov_b32_e32 v233, v179
	v_mov_b32_e32 v234, v179
	v_mov_b32_e32 v235, v179
	v_mov_b32_e32 v236, v179
	v_mov_b32_e32 v237, v179
	v_mov_b32_e32 v238, v179
	v_mov_b32_e32 v239, v179
	v_mov_b32_e32 v240, v179
	v_mov_b32_e32 v241, v179
	v_mov_b32_e32 v242, v179
	v_mov_b32_e32 v243, v179
	v_mov_b32_e32 v244, v179
	v_mov_b32_e32 v245, v179
	v_mov_b32_e32 v246, v179
	v_mov_b32_e32 v247, v179
	s_branch .LBB0_184
.LBB0_184:
	s_add_i32 s35, s35, 2
	s_min_u32 s36, s35, 0x7c
	s_add_i32 s41, s36, 3
	s_mul_i32 s36, s41, 0x3000
	s_add_u32 s36, s16, s36
	s_addc_u32 s37, s17, 0
	s_waitcnt lgkmcnt(0)
	s_barrier
	s_waitcnt vmcnt(9)
	ds_write_b128 v144, v[112:115] offset:13312
	s_waitcnt vmcnt(8)
	ds_write_b128 v145, v[116:119] offset:13312
	s_waitcnt vmcnt(6)
	ds_write_b128 v146, v[124:127] offset:13312
	ds_write_b128 v147, v[120:123] offset:35840
	s_waitcnt vmcnt(5)
	ds_write_b128 v148, v[128:131] offset:35840
	v_lshl_add_u64 v[36:37], v[34:35], 1, s[36:37]
	s_lshl_b32 s36, s41, 13
	global_load_dwordx4 v[112:115], v[36:37], off
	v_add_co_u32_e32 v36, vcc, s84, v36
	s_add_u32 s36, s18, s36
	s_nop 0
	v_addc_co_u32_e32 v37, vcc, 0, v37, vcc
	s_addc_u32 s37, s19, 0
	global_load_dwordx4 v[116:119], v[36:37], off offset:-4096
	global_load_dwordx4 v[124:127], v[36:37], off
	v_lshl_add_u64 v[36:37], v[134:135], 1, s[36:37]
	global_load_dwordx4 v[120:123], v[36:37], off
	v_add_co_u32_e32 v36, vcc, 0x1000, v36
	s_nop 1
	v_addc_co_u32_e32 v37, vcc, 0, v37, vcc
	global_load_dwordx4 v[128:131], v[36:37], off
	v_cmp_neq_f32_e32 vcc, 1.0, v138
	s_cbranch_vccz .Lmla_c0
	v_pk_mul_f32 v[32:33], v[138:139], v[32:33] op_sel_hi:[0,1]
	v_pk_mul_f32 v[30:31], v[138:139], v[30:31] op_sel_hi:[0,1]
	v_pk_mul_f32 v[28:29], v[138:139], v[28:29] op_sel_hi:[0,1]
	v_pk_mul_f32 v[26:27], v[138:139], v[26:27] op_sel_hi:[0,1]
	v_pk_mul_f32 v[24:25], v[138:139], v[24:25] op_sel_hi:[0,1]
	v_pk_mul_f32 v[22:23], v[138:139], v[22:23] op_sel_hi:[0,1]
	v_pk_mul_f32 v[20:21], v[138:139], v[20:21] op_sel_hi:[0,1]
	v_pk_mul_f32 v[18:19], v[138:139], v[18:19] op_sel_hi:[0,1]
	v_pk_mul_f32 v[16:17], v[138:139], v[16:17] op_sel_hi:[0,1]
	v_pk_mul_f32 v[14:15], v[138:139], v[14:15] op_sel_hi:[0,1]
	v_pk_mul_f32 v[12:13], v[138:139], v[12:13] op_sel_hi:[0,1]
	v_pk_mul_f32 v[10:11], v[138:139], v[10:11] op_sel_hi:[0,1]
	v_pk_mul_f32 v[8:9], v[138:139], v[8:9] op_sel_hi:[0,1]
	v_pk_mul_f32 v[6:7], v[138:139], v[6:7] op_sel_hi:[0,1]
	v_pk_mul_f32 v[4:5], v[138:139], v[4:5] op_sel_hi:[0,1]
	v_pk_mul_f32 v[2:3], v[138:139], v[2:3] op_sel_hi:[0,1]
	v_xor_b32_e32 v179, 0x80000000, v141
	v_mov_b32_e32 v232, v179
	v_mov_b32_e32 v233, v179
	v_mov_b32_e32 v234, v179
	v_mov_b32_e32 v235, v179
	v_mov_b32_e32 v236, v179
	v_mov_b32_e32 v237, v179
	v_mov_b32_e32 v238, v179
	v_mov_b32_e32 v239, v179
	v_mov_b32_e32 v240, v179
	v_mov_b32_e32 v241, v179
	v_mov_b32_e32 v242, v179
	v_mov_b32_e32 v243, v179
	v_mov_b32_e32 v244, v179
	v_mov_b32_e32 v245, v179
	v_mov_b32_e32 v246, v179
	v_mov_b32_e32 v247, v179
.Lmla_c0:
	ds_read_b128 v[152:155], v149
	ds_read_b128 v[156:159], v149 offset:32
	ds_read_b128 v[160:163], v149 offset:64
	ds_read_b128 v[164:167], v149 offset:96
	ds_read_b128 v[168:171], v149 offset:128
	ds_read_b128 v[172:175], v149 offset:160
	s_waitcnt lgkmcnt(5)
	v_mfma_f32_32x32x16_bf16 v[52:67], v[152:155], v[68:71], v[232:247]
	ds_read_b128 v[152:155], v149 offset:6656
	s_waitcnt lgkmcnt(5)
	v_mfma_f32_32x32x16_bf16 v[52:67], v[156:159], v[72:75], v[52:67]
	ds_read_b128 v[156:159], v149 offset:6688
	s_waitcnt lgkmcnt(5)
	v_mfma_f32_32x32x16_bf16 v[52:67], v[160:163], v[76:79], v[52:67]
	ds_read_b128 v[160:163], v149 offset:6720
	s_waitcnt lgkmcnt(5)
	v_mfma_f32_32x32x16_bf16 v[52:67], v[164:167], v[80:83], v[52:67]
	ds_read_b128 v[164:167], v149 offset:6752
	s_waitcnt lgkmcnt(5)
	v_mfma_f32_32x32x16_bf16 v[52:67], v[168:171], v[84:87], v[52:67]
	ds_read_b128 v[168:171], v149 offset:6784
	ds_read_b128 v[198:201], v150 offset:26624
	s_waitcnt lgkmcnt(6)
	v_mfma_f32_32x32x16_bf16 v[52:67], v[172:175], v[88:91], v[52:67]
	ds_read_b128 v[172:175], v149 offset:6816
	ds_read_b128 v[202:205], v150 offset:26656
	ds_read_b128 v[206:209], v150 offset:31232
	ds_read_b128 v[210:213], v150 offset:31264
	s_waitcnt lgkmcnt(9)
	v_mfma_f32_32x32x16_bf16 v[36:51], v[152:155], v[68:71], v[232:247]
	s_waitcnt lgkmcnt(8)
	v_mfma_f32_32x32x16_bf16 v[36:51], v[156:159], v[72:75], v[36:51]
	s_nop 3
	v_max3_f32 v178, v52, v53, v54
	v_max3_f32 v178, v178, v55, v56
	v_max3_f32 v178, v178, v57, v58
	v_max3_f32 v178, v178, v59, v60
	v_max3_f32 v178, v178, v61, v62
	v_max3_f32 v178, v178, v63, v64
	v_max3_f32 v178, v178, v65, v66
	v_max_f32_e32 v178, v178, v67
	v_exp_f32_e32 v52, v52
	v_exp_f32_e32 v53, v53
	s_waitcnt lgkmcnt(7)
	v_mfma_f32_32x32x16_bf16 v[36:51], v[160:163], v[76:79], v[36:51]
	v_exp_f32_e32 v54, v54
	v_exp_f32_e32 v55, v55
	v_exp_f32_e32 v56, v56
	v_exp_f32_e32 v57, v57
	v_exp_f32_e32 v58, v58
	v_exp_f32_e32 v59, v59
	s_waitcnt lgkmcnt(6)
	v_mfma_f32_32x32x16_bf16 v[36:51], v[164:167], v[80:83], v[36:51]
	v_exp_f32_e32 v60, v60
	v_exp_f32_e32 v61, v61
	v_exp_f32_e32 v62, v62
	v_exp_f32_e32 v63, v63
	v_exp_f32_e32 v64, v64
	v_exp_f32_e32 v65, v65
	s_waitcnt lgkmcnt(5)
	v_mfma_f32_32x32x16_bf16 v[36:51], v[168:171], v[84:87], v[36:51]
	v_exp_f32_e32 v66, v66
	v_exp_f32_e32 v67, v67
	v_add_f32_e32 v176, v52, v53
	v_add_f32_e32 v176, v54, v176
	v_add_f32_e32 v176, v55, v176
	v_add_f32_e32 v176, v56, v176
	v_add_f32_e32 v176, v57, v176
	v_add_f32_e32 v176, v58, v176
	v_add_f32_e32 v176, v59, v176
	s_waitcnt lgkmcnt(3)
	v_mfma_f32_32x32x16_bf16 v[36:51], v[172:175], v[88:91], v[36:51]
	v_add_f32_e32 v176, v60, v176
	v_add_f32_e32 v176, v61, v176
	v_add_f32_e32 v176, v62, v176
	v_add_f32_e32 v176, v63, v176
	v_add_f32_e32 v176, v64, v176
	v_add_f32_e32 v176, v65, v176
	v_add_f32_e32 v176, v66, v176
	v_add_f32_e32 v176, v67, v176
	v_cvt_pk_bf16_f32 v214, v52, v53
	v_cvt_pk_bf16_f32 v215, v54, v55
	v_cvt_pk_bf16_f32 v216, v56, v57
	v_cvt_pk_bf16_f32 v217, v58, v59
	v_cvt_pk_bf16_f32 v218, v60, v61
	v_cvt_pk_bf16_f32 v219, v62, v63
	v_cvt_pk_bf16_f32 v220, v64, v65
	v_cvt_pk_bf16_f32 v221, v66, v67
	v_mfma_f32_32x32x16_bf16 v[2:17], v[198:201], v[214:217], v[2:17]
	ds_read_b128 v[198:201], v150 offset:26688
	v_max3_f32 v178, v178, v36, v37
	v_max3_f32 v178, v178, v38, v39
	v_max3_f32 v178, v178, v40, v41
	v_max3_f32 v178, v178, v42, v43
	v_max3_f32 v178, v178, v44, v45
	v_max3_f32 v178, v178, v46, v47
	v_max3_f32 v178, v178, v48, v49
	v_max3_f32 v178, v178, v50, v51
	ds_bpermute_b32 v180, v143, v178
	s_waitcnt lgkmcnt(3)
	v_mfma_f32_32x32x16_bf16 v[18:33], v[206:209], v[214:217], v[18:33]
	ds_read_b128 v[206:209], v150 offset:31296
	v_exp_f32_e32 v36, v36
	v_exp_f32_e32 v37, v37
	v_exp_f32_e32 v38, v38
	v_exp_f32_e32 v39, v39
	v_exp_f32_e32 v40, v40
	v_exp_f32_e32 v41, v41
	v_mfma_f32_32x32x16_bf16 v[2:17], v[202:205], v[218:221], v[2:17]
	ds_read_b128 v[202:205], v150 offset:26720
	v_exp_f32_e32 v42, v42
	v_exp_f32_e32 v43, v43
	v_exp_f32_e32 v44, v44
	v_exp_f32_e32 v45, v45
	v_exp_f32_e32 v46, v46
	v_exp_f32_e32 v47, v47
	s_waitcnt lgkmcnt(4)
	v_mfma_f32_32x32x16_bf16 v[18:33], v[210:213], v[218:221], v[18:33]
	ds_read_b128 v[210:213], v150 offset:31328
	v_exp_f32_e32 v48, v48
	v_exp_f32_e32 v49, v49
	v_exp_f32_e32 v50, v50
	v_exp_f32_e32 v51, v51
	v_cvt_pk_bf16_f32 v222, v36, v37
	v_cvt_pk_bf16_f32 v223, v38, v39
	v_cvt_pk_bf16_f32 v224, v40, v41
	v_cvt_pk_bf16_f32 v225, v42, v43
	v_add_f32_e32 v177, v36, v37
	v_add_f32_e32 v177, v38, v177
	s_waitcnt lgkmcnt(4)
	v_mfma_f32_32x32x16_bf16 v[2:17], v[198:201], v[222:225], v[2:17]
	v_add_f32_e32 v177, v39, v177
	v_add_f32_e32 v177, v40, v177
	v_add_f32_e32 v177, v41, v177
	v_add_f32_e32 v177, v42, v177
	v_add_f32_e32 v177, v43, v177
	v_add_f32_e32 v177, v44, v177
	s_waitcnt lgkmcnt(2)
	v_mfma_f32_32x32x16_bf16 v[18:33], v[206:209], v[222:225], v[18:33]
	v_add_f32_e32 v177, v45, v177
	v_add_f32_e32 v177, v46, v177
	v_add_f32_e32 v177, v47, v177
	v_add_f32_e32 v177, v48, v177
	v_add_f32_e32 v177, v49, v177
	v_add_f32_e32 v177, v50, v177
	v_add_f32_e32 v177, v51, v177
	v_cvt_pk_bf16_f32 v226, v44, v45
	v_cvt_pk_bf16_f32 v227, v46, v47
	v_cvt_pk_bf16_f32 v228, v48, v49
	v_cvt_pk_bf16_f32 v229, v50, v51
	v_max_f32_e32 v180, v178, v180
	v_cmp_lt_f32_e32 vcc, 0x41000000, v180
	v_add_f32_e32 v176, v176, v177
	s_nop 0
	v_cndmask_b32_e32 v181, 0, v180, vcc
	s_waitcnt lgkmcnt(1)
	v_mfma_f32_32x32x16_bf16 v[2:17], v[202:205], v[226:229], v[2:17]
	v_fma_f32 v140, v140, v138, v176
	v_add_f32_e32 v141, v141, v181
	s_waitcnt lgkmcnt(0)
	v_mfma_f32_32x32x16_bf16 v[18:33], v[210:213], v[226:229], v[18:33]
	v_exp_f32_e64 v138, -v181
	s_add_i32 s36, s35, 4
	s_min_u32 s41, s36, 0x7f
	s_mul_i32 s36, s41, 0x3000
	s_add_u32 s36, s16, s36
	s_addc_u32 s37, s17, 0
	s_waitcnt lgkmcnt(0)
	s_barrier
; #define M2_STORE(S, buf) { M2_SK(0, S##k0, buf) M2_SK(1, S##k1, buf) M2_SK(2, S##k2, buf) M2_SV(0, S##v0, buf) M2_SV(1, S##v1, buf) }
; DI void flash_mla2(const bf16_t* __restrict__ Qp, const bf16_t* __restrict__ Kp, const bf16_t* __restrict__ Vtp,
;                    bf16_t* __restrict__ Op, char* smem, float& ssq) {
;     ...
;         M2_STORE(a, 0);
;         __syncthreads();
;         M2_LOAD(a, min(kt + 2, NKT - 1));
;         M2_COMPUTE(0);
;         M2_STORE(b, 1);
;         __syncthreads();
;         M2_LOAD(b, min(kt + 3, NKT - 1));
;         M2_COMPUTE(1);
	s_waitcnt vmcnt(9)
	ds_write_b128 v144, v[92:95]
	s_waitcnt vmcnt(8)
	ds_write_b128 v145, v[100:103]
	s_waitcnt vmcnt(6)
	ds_write_b128 v146, v[96:99]
	ds_write_b128 v147, v[104:107] offset:26624
	s_waitcnt vmcnt(5)
	ds_write_b128 v148, v[108:111] offset:26624
	v_lshl_add_u64 v[36:37], v[34:35], 1, s[36:37]
	s_lshl_b32 s36, s41, 13
	global_load_dwordx4 v[92:95], v[36:37], off
	v_add_co_u32_e32 v36, vcc, s84, v36
	s_add_u32 s36, s18, s36
	s_nop 0
	v_addc_co_u32_e32 v37, vcc, 0, v37, vcc
	s_addc_u32 s37, s19, 0
	global_load_dwordx4 v[100:103], v[36:37], off offset:-4096
	global_load_dwordx4 v[96:99], v[36:37], off
	v_lshl_add_u64 v[36:37], v[134:135], 1, s[36:37]
	global_load_dwordx4 v[104:107], v[36:37], off
	v_add_co_u32_e32 v36, vcc, 0x1000, v36
	s_nop 1
	v_addc_co_u32_e32 v37, vcc, 0, v37, vcc
	global_load_dwordx4 v[108:111], v[36:37], off
	v_cmp_neq_f32_e32 vcc, 1.0, v138
	s_cbranch_vccz .Lmla_c1
	v_pk_mul_f32 v[32:33], v[138:139], v[32:33] op_sel_hi:[0,1]
	v_pk_mul_f32 v[30:31], v[138:139], v[30:31] op_sel_hi:[0,1]
	v_pk_mul_f32 v[28:29], v[138:139], v[28:29] op_sel_hi:[0,1]
	v_pk_mul_f32 v[26:27], v[138:139], v[26:27] op_sel_hi:[0,1]
	v_pk_mul_f32 v[24:25], v[138:139], v[24:25] op_sel_hi:[0,1]
	v_pk_mul_f32 v[22:23], v[138:139], v[22:23] op_sel_hi:[0,1]
	v_pk_mul_f32 v[20:21], v[138:139], v[20:21] op_sel_hi:[0,1]
	v_pk_mul_f32 v[18:19], v[138:139], v[18:19] op_sel_hi:[0,1]
	v_pk_mul_f32 v[16:17], v[138:139], v[16:17] op_sel_hi:[0,1]
	v_pk_mul_f32 v[14:15], v[138:139], v[14:15] op_sel_hi:[0,1]
	v_pk_mul_f32 v[12:13], v[138:139], v[12:13] op_sel_hi:[0,1]
	v_pk_mul_f32 v[10:11], v[138:139], v[10:11] op_sel_hi:[0,1]
	v_pk_mul_f32 v[8:9], v[138:139], v[8:9] op_sel_hi:[0,1]
	v_pk_mul_f32 v[6:7], v[138:139], v[6:7] op_sel_hi:[0,1]
	v_pk_mul_f32 v[4:5], v[138:139], v[4:5] op_sel_hi:[0,1]
	v_pk_mul_f32 v[2:3], v[138:139], v[2:3] op_sel_hi:[0,1]
	v_xor_b32_e32 v179, 0x80000000, v141
	v_mov_b32_e32 v232, v179
	v_mov_b32_e32 v233, v179
	v_mov_b32_e32 v234, v179
	v_mov_b32_e32 v235, v179
	v_mov_b32_e32 v236, v179
	v_mov_b32_e32 v237, v179
	v_mov_b32_e32 v238, v179
	v_mov_b32_e32 v239, v179
	v_mov_b32_e32 v240, v179
	v_mov_b32_e32 v241, v179
	v_mov_b32_e32 v242, v179
	v_mov_b32_e32 v243, v179
	v_mov_b32_e32 v244, v179
	v_mov_b32_e32 v245, v179
	v_mov_b32_e32 v246, v179
	v_mov_b32_e32 v247, v179
; #define M2_STORE(S, buf) { M2_SK(0, S##k0, buf) M2_SK(1, S##k1, buf) M2_SK(2, S##k2, buf) M2_SV(0, S##v0, buf) M2_SV(1, S##v1, buf) }
; DI void flash_mla2(const bf16_t* __restrict__ Qp, const bf16_t* __restrict__ Kp, const bf16_t* __restrict__ Vtp,
;                    bf16_t* __restrict__ Op, char* smem, float& ssq) {
;     ...
;         M2_STORE(b, 1);
;         __syncthreads();
;         M2_LOAD(b, min(kt + 3, NKT - 1));
;         M2_COMPUTE(1);
;     }
.Lmla_c1:
	ds_read_b128 v[152:155], v149 offset:13312
	ds_read_b128 v[156:159], v149 offset:13344
	ds_read_b128 v[160:163], v149 offset:13376
	ds_read_b128 v[164:167], v149 offset:13408
	ds_read_b128 v[168:171], v149 offset:13440
	ds_read_b128 v[172:175], v149 offset:13472
	s_waitcnt lgkmcnt(5)
	v_mfma_f32_32x32x16_bf16 v[52:67], v[152:155], v[68:71], v[232:247]
	ds_read_b128 v[152:155], v149 offset:19968
	s_waitcnt lgkmcnt(5)
	v_mfma_f32_32x32x16_bf16 v[52:67], v[156:159], v[72:75], v[52:67]
	ds_read_b128 v[156:159], v149 offset:20000
	s_waitcnt lgkmcnt(5)
	v_mfma_f32_32x32x16_bf16 v[52:67], v[160:163], v[76:79], v[52:67]
	ds_read_b128 v[160:163], v149 offset:20032
	s_waitcnt lgkmcnt(5)
	v_mfma_f32_32x32x16_bf16 v[52:67], v[164:167], v[80:83], v[52:67]
	ds_read_b128 v[164:167], v149 offset:20064
	s_waitcnt lgkmcnt(5)
	v_mfma_f32_32x32x16_bf16 v[52:67], v[168:171], v[84:87], v[52:67]
	ds_read_b128 v[168:171], v149 offset:20096
	ds_read_b128 v[198:201], v150 offset:35840
	s_waitcnt lgkmcnt(6)
	v_mfma_f32_32x32x16_bf16 v[52:67], v[172:175], v[88:91], v[52:67]
	ds_read_b128 v[172:175], v149 offset:20128
	ds_read_b128 v[202:205], v150 offset:35872
	ds_read_b128 v[206:209], v150 offset:40448
	ds_read_b128 v[210:213], v150 offset:40480
	s_waitcnt lgkmcnt(9)
	v_mfma_f32_32x32x16_bf16 v[36:51], v[152:155], v[68:71], v[232:247]
	s_waitcnt lgkmcnt(8)
	v_mfma_f32_32x32x16_bf16 v[36:51], v[156:159], v[72:75], v[36:51]
	s_nop 3
	v_max3_f32 v178, v52, v53, v54
	v_max3_f32 v178, v178, v55, v56
	v_max3_f32 v178, v178, v57, v58
	v_max3_f32 v178, v178, v59, v60
	v_max3_f32 v178, v178, v61, v62
	v_max3_f32 v178, v178, v63, v64
	v_max3_f32 v178, v178, v65, v66
	v_max_f32_e32 v178, v178, v67
	v_exp_f32_e32 v52, v52
	v_exp_f32_e32 v53, v53
	s_waitcnt lgkmcnt(7)
	v_mfma_f32_32x32x16_bf16 v[36:51], v[160:163], v[76:79], v[36:51]
	v_exp_f32_e32 v54, v54
	v_exp_f32_e32 v55, v55
	v_exp_f32_e32 v56, v56
	v_exp_f32_e32 v57, v57
	v_exp_f32_e32 v58, v58
	v_exp_f32_e32 v59, v59
	s_waitcnt lgkmcnt(6)
	v_mfma_f32_32x32x16_bf16 v[36:51], v[164:167], v[80:83], v[36:51]
	v_exp_f32_e32 v60, v60
	v_exp_f32_e32 v61, v61
	v_exp_f32_e32 v62, v62
	v_exp_f32_e32 v63, v63
	v_exp_f32_e32 v64, v64
	v_exp_f32_e32 v65, v65
	s_waitcnt lgkmcnt(5)
	v_mfma_f32_32x32x16_bf16 v[36:51], v[168:171], v[84:87], v[36:51]
	v_exp_f32_e32 v66, v66
	v_exp_f32_e32 v67, v67
	v_add_f32_e32 v176, v52, v53
	v_add_f32_e32 v176, v54, v176
	v_add_f32_e32 v176, v55, v176
	v_add_f32_e32 v176, v56, v176
	v_add_f32_e32 v176, v57, v176
	v_add_f32_e32 v176, v58, v176
	v_add_f32_e32 v176, v59, v176
	s_waitcnt lgkmcnt(3)
	v_mfma_f32_32x32x16_bf16 v[36:51], v[172:175], v[88:91], v[36:51]
	v_add_f32_e32 v176, v60, v176
	v_add_f32_e32 v176, v61, v176
	v_add_f32_e32 v176, v62, v176
	v_add_f32_e32 v176, v63, v176
	v_add_f32_e32 v176, v64, v176
	v_add_f32_e32 v176, v65, v176
	v_add_f32_e32 v176, v66, v176
	v_add_f32_e32 v176, v67, v176
	v_cvt_pk_bf16_f32 v214, v52, v53
	v_cvt_pk_bf16_f32 v215, v54, v55
	v_cvt_pk_bf16_f32 v216, v56, v57
	v_cvt_pk_bf16_f32 v217, v58, v59
	v_cvt_pk_bf16_f32 v218, v60, v61
	v_cvt_pk_bf16_f32 v219, v62, v63
	v_cvt_pk_bf16_f32 v220, v64, v65
	v_cvt_pk_bf16_f32 v221, v66, v67
	v_mfma_f32_32x32x16_bf16 v[2:17], v[198:201], v[214:217], v[2:17]
	ds_read_b128 v[198:201], v150 offset:35904
	v_max3_f32 v178, v178, v36, v37
	v_max3_f32 v178, v178, v38, v39
	v_max3_f32 v178, v178, v40, v41
	v_max3_f32 v178, v178, v42, v43
	v_max3_f32 v178, v178, v44, v45
	v_max3_f32 v178, v178, v46, v47
	v_max3_f32 v178, v178, v48, v49
	v_max3_f32 v178, v178, v50, v51
	ds_bpermute_b32 v180, v143, v178
	s_waitcnt lgkmcnt(3)
	v_mfma_f32_32x32x16_bf16 v[18:33], v[206:209], v[214:217], v[18:33]
	ds_read_b128 v[206:209], v150 offset:40512
	v_exp_f32_e32 v36, v36
	v_exp_f32_e32 v37, v37
	v_exp_f32_e32 v38, v38
	v_exp_f32_e32 v39, v39
	v_exp_f32_e32 v40, v40
	v_exp_f32_e32 v41, v41
	v_mfma_f32_32x32x16_bf16 v[2:17], v[202:205], v[218:221], v[2:17]
	ds_read_b128 v[202:205], v150 offset:35936
	v_exp_f32_e32 v42, v42
	v_exp_f32_e32 v43, v43
	v_exp_f32_e32 v44, v44
	v_exp_f32_e32 v45, v45
	v_exp_f32_e32 v46, v46
	v_exp_f32_e32 v47, v47
	s_waitcnt lgkmcnt(4)
	v_mfma_f32_32x32x16_bf16 v[18:33], v[210:213], v[218:221], v[18:33]
	ds_read_b128 v[210:213], v150 offset:40544
	v_exp_f32_e32 v48, v48
	v_exp_f32_e32 v49, v49
	v_exp_f32_e32 v50, v50
	v_exp_f32_e32 v51, v51
	v_cvt_pk_bf16_f32 v222, v36, v37
	v_cvt_pk_bf16_f32 v223, v38, v39
	v_cvt_pk_bf16_f32 v224, v40, v41
	v_cvt_pk_bf16_f32 v225, v42, v43
	v_add_f32_e32 v177, v36, v37
	v_add_f32_e32 v177, v38, v177
	s_waitcnt lgkmcnt(4)
	v_mfma_f32_32x32x16_bf16 v[2:17], v[198:201], v[222:225], v[2:17]
	v_add_f32_e32 v177, v39, v177
	v_add_f32_e32 v177, v40, v177
	v_add_f32_e32 v177, v41, v177
	v_add_f32_e32 v177, v42, v177
	v_add_f32_e32 v177, v43, v177
	v_add_f32_e32 v177, v44, v177
	s_waitcnt lgkmcnt(2)
	v_mfma_f32_32x32x16_bf16 v[18:33], v[206:209], v[222:225], v[18:33]
	v_add_f32_e32 v177, v45, v177
	v_add_f32_e32 v177, v46, v177
	v_add_f32_e32 v177, v47, v177
	v_add_f32_e32 v177, v48, v177
	v_add_f32_e32 v177, v49, v177
	v_add_f32_e32 v177, v50, v177
	v_add_f32_e32 v177, v51, v177
	v_cvt_pk_bf16_f32 v226, v44, v45
	v_cvt_pk_bf16_f32 v227, v46, v47
	v_cvt_pk_bf16_f32 v228, v48, v49
	v_cvt_pk_bf16_f32 v229, v50, v51
	v_max_f32_e32 v180, v178, v180
	v_cmp_lt_f32_e32 vcc, 0x41000000, v180
	v_add_f32_e32 v176, v176, v177
	s_nop 0
	v_cndmask_b32_e32 v181, 0, v180, vcc
	s_waitcnt lgkmcnt(1)
	v_mfma_f32_32x32x16_bf16 v[2:17], v[202:205], v[226:229], v[2:17]
	v_fma_f32 v140, v140, v138, v176
	v_add_f32_e32 v141, v141, v181
	s_waitcnt lgkmcnt(0)
	v_mfma_f32_32x32x16_bf16 v[18:33], v[210:213], v[226:229], v[18:33]
	v_exp_f32_e64 v138, -v181
	s_cmpk_lt_u32 s35, 0x7e
	s_cbranch_scc1 .LBB0_184
	s_branch .LBB0_181

; DI int tid() { int t = threadIdx.x; asm volatile("" : "+v"(t)); return t; }
; DI int crow(int r, int h) { return (r & 3) + 8 * (r >> 2) + 4 * h; }
; DI float* stage_tile(const f32x16 (&acc)[2][2], const float* rs, char* smem) {
;     const int tt = tid(), lane = tt & 63, w = __builtin_amdgcn_readfirstlane(tt >> 6), wm = w >> 1, wn = w & 1, l32 = lane & 31, h = lane >> 5;
;     float* stg = (float*)smem;
; #pragma unroll
;     for (int i = 0; i < 2; ++i)
; #pragma unroll
;         for (int j = 0; j < 2; ++j)
; #pragma unroll
;             for (int r = 0; r < 16; ++r) {
;                 const int row = wm * 64 + i * 32 + crow(r, h);
;                 stg[row * 132 + wn * 64 + j * 32 + l32] = rs ? acc[i][j][r] * rs[row] : acc[i][j][r];
;             }
;     __syncthreads();
;     return stg;
; }
.LBB0_202:
	s_or_b64 exec, exec, s[16:17]
	v_mov_b32_e32 v32, v182
	s_waitcnt lgkmcnt(0)
	s_barrier
	s_and_b32 s8, s8, -8
	v_readfirstlane_b32 s11, v32
	v_and_b32_e32 v33, 31, v32
	s_ashr_i32 s12, s11, 1
	v_lshrrev_b32_e32 v32, 3, v32
	s_andn2_b32 s12, s12, 63
	v_and_b32_e32 v68, 4, v32
	v_and_or_b32 v32, s11, 64, v33
	v_or_b32_e32 v33, s12, v68
	s_add_i32 s11, 0, 0x12000
	v_lshl_add_u32 v69, v33, 2, s11
	ds_read_b32 v34, v69
	v_mul_lo_u32 v33, v33, s82
	v_lshlrev_b32_e32 v32, 2, v32
	v_or_b32_e32 v71, 1, v68
	v_add3_u32 v70, 0, v33, v32
	s_waitcnt lgkmcnt(0)
	v_mul_f32_e32 v34, v52, v34
	v_or_b32_e32 v33, s12, v71
	ds_write_b32 v70, v34
	v_lshl_add_u32 v72, v33, 2, s11
	ds_read_b32 v34, v72
	v_mul_lo_u32 v33, v33, s82
	v_or_b32_e32 v74, 2, v68
	v_add3_u32 v73, 0, v33, v32
	v_or_b32_e32 v33, s12, v74
	s_waitcnt lgkmcnt(0)
	v_mul_f32_e32 v34, v53, v34
	ds_write_b32 v73, v34
	v_lshl_add_u32 v75, v33, 2, s11
	ds_read_b32 v34, v75
	v_mul_lo_u32 v33, v33, s82
	v_or_b32_e32 v77, 3, v68
	v_add3_u32 v76, 0, v33, v32
	v_or_b32_e32 v33, s12, v77
	s_waitcnt lgkmcnt(0)
	v_mul_f32_e32 v34, v54, v34
	ds_write_b32 v76, v34
	v_lshl_add_u32 v78, v33, 2, s11
	ds_read_b32 v34, v78
	v_mul_lo_u32 v33, v33, s82
	v_or_b32_e32 v79, 8, v68
	v_or_b32_e32 v81, 9, v68
	v_or_b32_e32 v83, 10, v68
	s_waitcnt lgkmcnt(0)
	v_mul_f32_e32 v34, v55, v34
	v_add3_u32 v55, 0, v33, v32
	v_or_b32_e32 v33, s12, v79
	ds_write_b32 v55, v34
	v_lshl_add_u32 v80, v33, 2, s11
	ds_read_b32 v34, v80
	v_mul_lo_u32 v33, v33, s82
	v_or_b32_e32 v85, 11, v68
	v_or_b32_e32 v87, 16, v68
	v_or_b32_e32 v89, 17, v68
	s_waitcnt lgkmcnt(0)
	v_mul_f32_e32 v34, v56, v34
	v_add3_u32 v56, 0, v33, v32
	v_or_b32_e32 v33, s12, v81
	ds_write_b32 v56, v34
	v_lshl_add_u32 v82, v33, 2, s11
	ds_read_b32 v34, v82
	v_mul_lo_u32 v33, v33, s82
	v_or_b32_e32 v91, 18, v68
	v_or_b32_e32 v54, 19, v68
	v_or_b32_e32 v53, 24, v68
	s_waitcnt lgkmcnt(0)
	v_mul_f32_e32 v34, v57, v34
	v_add3_u32 v57, 0, v33, v32
	v_or_b32_e32 v33, s12, v83
	ds_write_b32 v57, v34
	v_lshl_add_u32 v84, v33, 2, s11
	ds_read_b32 v34, v84
	v_mul_lo_u32 v33, v33, s82
	v_or_b32_e32 v52, 25, v68
	s_add_i32 s8, s9, s8
	s_ashr_i32 s9, s8, 31
	s_waitcnt lgkmcnt(0)
	v_mul_f32_e32 v34, v58, v34
	v_add3_u32 v58, 0, v33, v32
	v_or_b32_e32 v33, s12, v85
	ds_write_b32 v58, v34
	v_lshl_add_u32 v86, v33, 2, s11
	ds_read_b32 v34, v86
	v_mul_lo_u32 v33, v33, s82
	s_and_b32 s16, s10, 0x1f80
	s_waitcnt lgkmcnt(0)
	v_mul_f32_e32 v34, v59, v34
	v_add3_u32 v59, 0, v33, v32
	v_or_b32_e32 v33, s12, v87
	ds_write_b32 v59, v34
	v_lshl_add_u32 v88, v33, 2, s11
	ds_read_b32 v34, v88
	v_mul_lo_u32 v33, v33, s82
	s_waitcnt lgkmcnt(0)
	v_mul_f32_e32 v34, v60, v34
	v_add3_u32 v60, 0, v33, v32
	v_or_b32_e32 v33, s12, v89
	ds_write_b32 v60, v34
	v_lshl_add_u32 v90, v33, 2, s11
	ds_read_b32 v34, v90
	v_mul_lo_u32 v33, v33, s82
	s_waitcnt lgkmcnt(0)
	v_mul_f32_e32 v34, v61, v34
	v_add3_u32 v61, 0, v33, v32
	v_or_b32_e32 v33, s12, v91
	ds_write_b32 v61, v34
	v_lshl_add_u32 v92, v33, 2, s11
	ds_read_b32 v34, v92
	v_mul_lo_u32 v33, v33, s82
	s_waitcnt lgkmcnt(0)
	v_mul_f32_e32 v34, v62, v34
	v_add3_u32 v62, 0, v33, v32
	v_or_b32_e32 v33, s12, v54
	ds_write_b32 v62, v34
	v_lshl_add_u32 v93, v33, 2, s11
	ds_read_b32 v34, v93
	v_mul_lo_u32 v33, v33, s82
	s_waitcnt lgkmcnt(0)
	v_mul_f32_e32 v34, v63, v34
	v_add3_u32 v63, 0, v33, v32
	v_or_b32_e32 v33, s12, v53
	ds_write_b32 v63, v34
	v_lshl_add_u32 v94, v33, 2, s11
	ds_read_b32 v34, v94
	v_mul_lo_u32 v33, v33, s82
	s_waitcnt lgkmcnt(0)
	v_mul_f32_e32 v34, v64, v34
	v_add3_u32 v64, 0, v33, v32
	v_or_b32_e32 v33, s12, v52
	ds_write_b32 v64, v34
	v_lshl_add_u32 v95, v33, 2, s11
	ds_read_b32 v34, v95
	v_mul_lo_u32 v33, v33, s82
	s_waitcnt lgkmcnt(0)
	v_mul_f32_e32 v34, v65, v34
	v_add3_u32 v65, 0, v33, v32
	ds_write_b32 v65, v34
	v_or_b32_e32 v34, 26, v68
	v_or_b32_e32 v33, s12, v34
	v_lshl_add_u32 v96, v33, 2, s11
	ds_read_b32 v97, v96
	v_mul_lo_u32 v33, v33, s82
	s_waitcnt lgkmcnt(0)
	v_mul_f32_e32 v66, v66, v97
	v_add3_u32 v97, 0, v33, v32
	v_or_b32_e32 v33, 27, v68
	ds_write_b32 v97, v66
	v_or_b32_e32 v66, s12, v33
	v_lshl_add_u32 v98, v66, 2, s11
	ds_read_b32 v99, v98
	v_mul_lo_u32 v66, v66, s82
	v_add3_u32 v66, 0, v66, v32
	s_or_b32 s12, s12, 32
	s_waitcnt lgkmcnt(0)
	v_mul_f32_e32 v67, v67, v99
	ds_write_b32 v66, v67
	ds_read_b32 v67, v69
	s_waitcnt lgkmcnt(0)
	v_mul_f32_e32 v36, v36, v67
	ds_write_b32 v70, v36 offset:128
	ds_read_b32 v36, v72
	s_waitcnt lgkmcnt(0)
	v_mul_f32_e32 v36, v37, v36
	ds_write_b32 v73, v36 offset:128
	ds_read_b32 v36, v75
	v_or_b32_e32 v37, s12, v68
	s_waitcnt lgkmcnt(0)
	v_mul_f32_e32 v36, v38, v36
	ds_write_b32 v76, v36 offset:128
	ds_read_b32 v36, v78
	s_waitcnt lgkmcnt(0)
	v_mul_f32_e32 v36, v39, v36
	ds_write_b32 v55, v36 offset:128
	ds_read_b32 v36, v80
	s_waitcnt lgkmcnt(0)
	v_mul_f32_e32 v36, v40, v36
	ds_write_b32 v56, v36 offset:128
	ds_read_b32 v36, v82
	s_waitcnt lgkmcnt(0)
	v_mul_f32_e32 v36, v41, v36
	ds_write_b32 v57, v36 offset:128
	ds_read_b32 v36, v84
	s_waitcnt lgkmcnt(0)
	v_mul_f32_e32 v36, v42, v36
	ds_write_b32 v58, v36 offset:128
	ds_read_b32 v36, v86
	s_waitcnt lgkmcnt(0)
	v_mul_f32_e32 v36, v43, v36
	ds_write_b32 v59, v36 offset:128
	ds_read_b32 v36, v88
	s_waitcnt lgkmcnt(0)
	v_mul_f32_e32 v36, v44, v36
	ds_write_b32 v60, v36 offset:128
	ds_read_b32 v36, v90
	s_waitcnt lgkmcnt(0)
	v_mul_f32_e32 v36, v45, v36
	ds_write_b32 v61, v36 offset:128
	ds_read_b32 v36, v92
	s_waitcnt lgkmcnt(0)
	v_mul_f32_e32 v36, v46, v36
	ds_write_b32 v62, v36 offset:128
	ds_read_b32 v36, v93
	s_waitcnt lgkmcnt(0)
	v_mul_f32_e32 v36, v47, v36
	ds_write_b32 v63, v36 offset:128
	ds_read_b32 v36, v94
	s_waitcnt lgkmcnt(0)
; DI unsigned pack2(float a, float b) { f32v2_t v = {a, b}; return __builtin_bit_cast(unsigned, __builtin_convertvector(v, bf16v2_t)); }
; DI int tid() { int t = threadIdx.x; asm volatile("" : "+v"(t)); return t; }
; DI int crow(int r, int h) { return (r & 3) + 8 * (r >> 2) + 4 * h; }
; DI void st_nt16(void* p, const uint4& v) { u32x4 t = {v.x, v.y, v.z, v.w}; __builtin_nontemporal_store(t, (u32x4*)p); }
; DI float* stage_tile(const f32x16 (&acc)[2][2], const float* rs, char* smem) {
;     const int tt = tid(), lane = tt & 63, w = __builtin_amdgcn_readfirstlane(tt >> 6), wm = w >> 1, wn = w & 1, l32 = lane & 31, h = lane >> 5;
;     float* stg = (float*)smem;
; #pragma unroll
;     for (int i = 0; i < 2; ++i)
; #pragma unroll
;         for (int j = 0; j < 2; ++j)
; #pragma unroll
;             for (int r = 0; r < 16; ++r) {
;                 const int row = wm * 64 + i * 32 + crow(r, h);
;                 stg[row * 132 + wn * 64 + j * 32 + l32] = rs ? acc[i][j][r] * rs[row] : acc[i][j][r];
;             }
;     __syncthreads();
;     return stg;
; }
; DI void ph_qkv(KP p, int l, char* smem) {
;     ...
;             const int tt = tid(), tok0 = rt * 128, b = tok0 >> 13, s0 = tok0 & 8191;
;             {
;                 const int c8 = tt & 7;
; #pragma unroll
;                 for (int i = 0; i < 4; ++i) {
;                     const int row = (tt >> 3) + 32 * i;
;                     const float4 lo = *(const float4*)(stg + row * 132 + c8 * 8), hi = *(const float4*)(stg + row * 132 + c8 * 8 + 4);
;                     st_nt16((bf16_t*)(p->ws + OFF_K) + (((size_t)(b * 8 + c2)) * SEQ + s0 + row) * 96 + c8 * 8, pack8(lo, hi));
;                 }
;             }
;             {
;                 const int tc = tt & 15;
; #pragma unroll
;                 for (int i = 0; i < 4; ++i) {
;                     const int d = (tt >> 4) + 16 * i;
;                     const float* sp = stg + (tc * 8) * 132 + 64 + d;
;                     uint4 ov;
;                     ov.x = pack2(sp[0], sp[132]); ov.y = pack2(sp[2 * 132], sp[3 * 132]); ov.z = pack2(sp[4 * 132], sp[5 * 132]); ov.w = pack2(sp[6 * 132], sp[7 * 132]);
;                     st_nt16((bf16_t*)(p->ws + OFF_VT) + (((size_t)(b * 8 + c2)) * 64 + d) * SEQ + s0 + tc * 8, ov);
	v_mul_f32_e32 v36, v48, v36
	ds_write_b32 v64, v36 offset:128
	ds_read_b32 v36, v95
	s_waitcnt lgkmcnt(0)
	v_mul_f32_e32 v36, v49, v36
	ds_write_b32 v65, v36 offset:128
	ds_read_b32 v36, v96
	s_waitcnt lgkmcnt(0)
	v_mul_f32_e32 v36, v50, v36
	ds_write_b32 v97, v36 offset:128
	ds_read_b32 v36, v98
	s_waitcnt lgkmcnt(0)
	v_mul_f32_e32 v36, v51, v36
	ds_write_b32 v66, v36 offset:128
	v_lshl_add_u32 v36, v37, 2, s11
	ds_read_b32 v38, v36
	s_waitcnt lgkmcnt(0)
	v_mul_f32_e32 v38, v16, v38
	v_mul_lo_u32 v16, v37, s82
	v_add3_u32 v16, 0, v16, v32
	ds_write_b32 v16, v38
	v_or_b32_e32 v38, s12, v71
	v_lshl_add_u32 v37, v38, 2, s11
	ds_read_b32 v39, v37
	s_waitcnt lgkmcnt(0)
	v_mul_f32_e32 v39, v17, v39
	v_mul_lo_u32 v17, v38, s82
	v_add3_u32 v17, 0, v17, v32
	ds_write_b32 v17, v39
	v_or_b32_e32 v39, s12, v74
	v_lshl_add_u32 v38, v39, 2, s11
	ds_read_b32 v40, v38
	s_waitcnt lgkmcnt(0)
	v_mul_f32_e32 v40, v18, v40
	v_mul_lo_u32 v18, v39, s82
	v_add3_u32 v18, 0, v18, v32
	v_or_b32_e32 v39, s12, v77
	ds_write_b32 v18, v40
	v_lshl_add_u32 v40, v39, 2, s11
	ds_read_b32 v41, v40
	v_mul_lo_u32 v39, v39, s82
	v_add3_u32 v39, 0, v39, v32
	s_waitcnt lgkmcnt(0)
	v_mul_f32_e32 v19, v19, v41
	ds_write_b32 v39, v19
	v_or_b32_e32 v19, s12, v79
	v_lshl_add_u32 v41, v19, 2, s11
	ds_read_b32 v42, v41
	v_mul_lo_u32 v19, v19, s82
	v_add3_u32 v19, 0, v19, v32
	s_waitcnt lgkmcnt(0)
	v_mul_f32_e32 v20, v20, v42
	ds_write_b32 v19, v20
	v_or_b32_e32 v20, s12, v81
	v_lshl_add_u32 v42, v20, 2, s11
	ds_read_b32 v43, v42
	v_mul_lo_u32 v20, v20, s82
	v_add3_u32 v20, 0, v20, v32
	s_waitcnt lgkmcnt(0)
	v_mul_f32_e32 v21, v21, v43
	ds_write_b32 v20, v21
	v_or_b32_e32 v21, s12, v83
	v_lshl_add_u32 v43, v21, 2, s11
	ds_read_b32 v44, v43
	v_mul_lo_u32 v21, v21, s82
	v_add3_u32 v21, 0, v21, v32
	s_waitcnt lgkmcnt(0)
	v_mul_f32_e32 v22, v22, v44
	ds_write_b32 v21, v22
	v_or_b32_e32 v22, s12, v85
	v_lshl_add_u32 v44, v22, 2, s11
	ds_read_b32 v45, v44
	v_mul_lo_u32 v22, v22, s82
	v_add3_u32 v22, 0, v22, v32
	s_waitcnt lgkmcnt(0)
	v_mul_f32_e32 v23, v23, v45
	ds_write_b32 v22, v23
	v_or_b32_e32 v23, s12, v87
	v_lshl_add_u32 v45, v23, 2, s11
	ds_read_b32 v46, v45
	v_mul_lo_u32 v23, v23, s82
	v_add3_u32 v23, 0, v23, v32
	s_waitcnt lgkmcnt(0)
	v_mul_f32_e32 v24, v24, v46
	ds_write_b32 v23, v24
	v_or_b32_e32 v24, s12, v89
	v_lshl_add_u32 v46, v24, 2, s11
	ds_read_b32 v47, v46
	v_mul_lo_u32 v24, v24, s82
	v_add3_u32 v24, 0, v24, v32
	s_waitcnt lgkmcnt(0)
	v_mul_f32_e32 v25, v25, v47
	ds_write_b32 v24, v25
	v_or_b32_e32 v25, s12, v91
	v_lshl_add_u32 v47, v25, 2, s11
	ds_read_b32 v48, v47
	v_mul_lo_u32 v25, v25, s82
	v_add3_u32 v25, 0, v25, v32
	s_waitcnt lgkmcnt(0)
	v_mul_f32_e32 v26, v26, v48
	ds_write_b32 v25, v26
	v_or_b32_e32 v26, s12, v54
	v_lshl_add_u32 v48, v26, 2, s11
	ds_read_b32 v49, v48
	v_mul_lo_u32 v26, v26, s82
	v_add3_u32 v26, 0, v26, v32
	s_waitcnt lgkmcnt(0)
	v_mul_f32_e32 v27, v27, v49
	ds_write_b32 v26, v27
	v_or_b32_e32 v27, s12, v53
	v_lshl_add_u32 v49, v27, 2, s11
	ds_read_b32 v50, v49
	v_mul_lo_u32 v27, v27, s82
	v_add3_u32 v27, 0, v27, v32
	s_waitcnt lgkmcnt(0)
	v_mul_f32_e32 v28, v28, v50
	ds_write_b32 v27, v28
	v_or_b32_e32 v28, s12, v52
	v_lshl_add_u32 v50, v28, 2, s11
	ds_read_b32 v51, v50
	v_mul_lo_u32 v28, v28, s82
	v_add3_u32 v28, 0, v28, v32
	s_waitcnt lgkmcnt(0)
	v_mul_f32_e32 v29, v29, v51
	ds_write_b32 v28, v29
	v_or_b32_e32 v29, s12, v34
	v_lshl_add_u32 v34, v29, 2, s11
	ds_read_b32 v51, v34
	v_mul_lo_u32 v29, v29, s82
	v_add3_u32 v29, 0, v29, v32
	s_waitcnt lgkmcnt(0)
	v_mul_f32_e32 v30, v30, v51
	ds_write_b32 v29, v30
	v_or_b32_e32 v30, s12, v33
	v_lshl_add_u32 v33, v30, 2, s11
	ds_read_b32 v51, v33
	v_mul_lo_u32 v30, v30, s82
	v_add3_u32 v30, 0, v30, v32
	s_lshl_b64 s[10:11], s[8:9], 13
	s_or_b32 s10, s10, s16
	s_waitcnt lgkmcnt(0)
	v_mul_f32_e32 v31, v31, v51
	ds_write_b32 v30, v31
	ds_read_b32 v31, v36
	s_add_u32 s12, s14, 0x10180000
	s_addc_u32 s13, s15, 0
	s_lshl_b64 s[8:9], s[8:9], 20
	s_add_u32 s8, s14, s8
	s_waitcnt lgkmcnt(0)
	v_mul_f32_e32 v0, v0, v31
	ds_write_b32 v16, v0 offset:128
	ds_read_b32 v0, v37
	v_mov_b32_e32 v16, v182
	s_addc_u32 s9, s15, s9
	s_lshl_b32 s56, s16, 7
	s_mov_b64 s[14:15], 0
	s_waitcnt lgkmcnt(0)
	v_mul_f32_e32 v0, v1, v0
	ds_write_b32 v17, v0 offset:128
	ds_read_b32 v0, v38
	s_waitcnt lgkmcnt(0)
	v_mul_f32_e32 v0, v2, v0
	ds_write_b32 v18, v0 offset:128
	ds_read_b32 v0, v40
	s_waitcnt lgkmcnt(0)
	v_mul_f32_e32 v0, v3, v0
	ds_write_b32 v39, v0 offset:128
	ds_read_b32 v0, v41
	s_waitcnt lgkmcnt(0)
	v_mul_f32_e32 v0, v4, v0
	ds_write_b32 v19, v0 offset:128
	ds_read_b32 v0, v42
	s_waitcnt lgkmcnt(0)
	v_mul_f32_e32 v0, v5, v0
	ds_write_b32 v20, v0 offset:128
	ds_read_b32 v0, v43
	s_waitcnt lgkmcnt(0)
	v_mul_f32_e32 v0, v6, v0
	ds_write_b32 v21, v0 offset:128
	ds_read_b32 v0, v44
	s_waitcnt lgkmcnt(0)
	v_mul_f32_e32 v0, v7, v0
	ds_write_b32 v22, v0 offset:128
	ds_read_b32 v0, v45
	s_waitcnt lgkmcnt(0)
	v_mul_f32_e32 v0, v8, v0
	ds_write_b32 v23, v0 offset:128
	ds_read_b32 v0, v46
	s_waitcnt lgkmcnt(0)
	v_mul_f32_e32 v0, v9, v0
	ds_write_b32 v24, v0 offset:128
	ds_read_b32 v0, v47
	s_waitcnt lgkmcnt(0)
	v_mul_f32_e32 v0, v10, v0
	ds_write_b32 v25, v0 offset:128
	ds_read_b32 v0, v48
	s_waitcnt lgkmcnt(0)
	v_mul_f32_e32 v0, v11, v0
	ds_write_b32 v26, v0 offset:128
	ds_read_b32 v0, v49
	s_waitcnt lgkmcnt(0)
	v_mul_f32_e32 v0, v12, v0
	ds_write_b32 v27, v0 offset:128
	ds_read_b32 v0, v50
	s_waitcnt lgkmcnt(0)
	v_mul_f32_e32 v0, v13, v0
	ds_write_b32 v28, v0 offset:128
	ds_read_b32 v0, v34
	v_mov_b64_e32 v[12:13], s[12:13]
	s_waitcnt lgkmcnt(0)
	v_mul_f32_e32 v0, v14, v0
	ds_write_b32 v29, v0 offset:128
	ds_read_b32 v0, v33
	s_waitcnt lgkmcnt(0)
	v_mul_f32_e32 v0, v15, v0
	ds_write_b32 v30, v0 offset:128
	s_waitcnt lgkmcnt(0)
	s_barrier
; DI unsigned pack2(float a, float b) { f32v2_t v = {a, b}; return __builtin_bit_cast(unsigned, __builtin_convertvector(v, bf16v2_t)); }
; DI int tid() { int t = threadIdx.x; asm volatile("" : "+v"(t)); return t; }
; DI void st_nt16(void* p, const uint4& v) { u32x4 t = {v.x, v.y, v.z, v.w}; __builtin_nontemporal_store(t, (u32x4*)p); }
; DI uint4 pack8(const float4& a, const float4& b) { uint4 o; o.x = pack2(a.x, a.y); o.y = pack2(a.z, a.w); o.z = pack2(b.x, b.y); o.w = pack2(b.z, b.w); return o; }
; DI void ph_qkv(KP p, int l, char* smem) {
;     ...
;             const int tt = tid(), tok0 = rt * 128, b = tok0 >> 13, s0 = tok0 & 8191;
;             {
;                 const int c8 = tt & 7;
; #pragma unroll
;                 for (int i = 0; i < 4; ++i) {
;                     const int row = (tt >> 3) + 32 * i;
;                     const float4 lo = *(const float4*)(stg + row * 132 + c8 * 8), hi = *(const float4*)(stg + row * 132 + c8 * 8 + 4);
;                     st_nt16((bf16_t*)(p->ws + OFF_K) + (((size_t)(b * 8 + c2)) * SEQ + s0 + row) * 96 + c8 * 8, pack8(lo, hi));
;                 }
;             }
;             {
;                 const int tc = tt & 15;
; #pragma unroll
;                 for (int i = 0; i < 4; ++i) {
;                     const int d = (tt >> 4) + 16 * i;
;                     const float* sp = stg + (tc * 8) * 132 + 64 + d;
;                     uint4 ov;
;                     ov.x = pack2(sp[0], sp[132]); ov.y = pack2(sp[2 * 132], sp[3 * 132]); ov.z = pack2(sp[4 * 132], sp[5 * 132]); ov.w = pack2(sp[6 * 132], sp[7 * 132]);
;                     st_nt16((bf16_t*)(p->ws + OFF_VT) + (((size_t)(b * 8 + c2)) * 64 + d) * SEQ + s0 + tc * 8, ov);
;                 }
;             }
	s_nop 0
	v_lshlrev_b32_e32 v17, 3, v16
	v_ashrrev_i32_e32 v8, 3, v16
	v_and_b32_e32 v18, 56, v17
	v_lshlrev_b32_e32 v0, 2, v18
	v_mul_lo_u32 v1, v8, s82
	v_add3_u32 v19, 0, v0, v1
	ds_read_b128 v[0:3], v19
	ds_read_b128 v[4:7], v19 offset:16
	v_ashrrev_i32_e32 v9, 31, v8
	v_lshl_add_u64 v[10:11], s[10:11], 0, v[8:9]
	v_mad_u64_u32 v[14:15], s[12:13], v10, s86, v[12:13]
	v_mad_i32_i24 v15, v11, s86, v15
	v_lshlrev_b32_e32 v34, 1, v18
	v_lshl_add_u64 v[10:11], v[14:15], 0, v[34:35]
	s_waitcnt lgkmcnt(1)
	v_cvt_pk_bf16_f32 v0, v0, v1
	v_cvt_pk_bf16_f32 v1, v2, v3
	s_waitcnt lgkmcnt(0)
	v_cvt_pk_bf16_f32 v2, v4, v5
	v_cvt_pk_bf16_f32 v3, v6, v7
	global_store_dwordx4 v[10:11], v[0:3], off nt
	v_add_u32_e32 v10, 32, v8
	ds_read_b128 v[0:3], v19 offset:16896
	ds_read_b128 v[4:7], v19 offset:16912
	v_ashrrev_i32_e32 v11, 31, v10
	v_lshl_add_u64 v[10:11], s[10:11], 0, v[10:11]
	v_mad_u64_u32 v[14:15], s[12:13], v10, s86, v[12:13]
	v_mad_i32_i24 v15, v11, s86, v15
	v_lshl_add_u64 v[10:11], v[14:15], 0, v[34:35]
	s_waitcnt lgkmcnt(1)
	v_cvt_pk_bf16_f32 v0, v0, v1
	v_cvt_pk_bf16_f32 v1, v2, v3
	s_waitcnt lgkmcnt(0)
	v_cvt_pk_bf16_f32 v2, v4, v5
	v_cvt_pk_bf16_f32 v3, v6, v7
	global_store_dwordx4 v[10:11], v[0:3], off nt
	v_add_u32_e32 v10, 64, v8
	ds_read_b128 v[0:3], v19 offset:33792
	ds_read_b128 v[4:7], v19 offset:33808
	v_ashrrev_i32_e32 v11, 31, v10
	v_lshl_add_u64 v[10:11], s[10:11], 0, v[10:11]
	v_mad_u64_u32 v[14:15], s[12:13], v10, s86, v[12:13]
	v_mad_i32_i24 v15, v11, s86, v15
	v_lshl_add_u64 v[10:11], v[14:15], 0, v[34:35]
	s_waitcnt lgkmcnt(1)
	v_cvt_pk_bf16_f32 v0, v0, v1
	v_cvt_pk_bf16_f32 v1, v2, v3
	s_waitcnt lgkmcnt(0)
	v_cvt_pk_bf16_f32 v2, v4, v5
	v_cvt_pk_bf16_f32 v3, v6, v7
	global_store_dwordx4 v[10:11], v[0:3], off nt
	v_add_u32_e32 v8, 0x60, v8
	ds_read_b128 v[0:3], v19 offset:50688
	ds_read_b128 v[4:7], v19 offset:50704
	v_ashrrev_i32_e32 v9, 31, v8
	v_lshl_add_u64 v[8:9], s[10:11], 0, v[8:9]
	v_mad_u64_u32 v[10:11], s[10:11], v8, s86, v[12:13]
	v_mad_i32_i24 v11, v9, s86, v11
	v_lshl_add_u64 v[8:9], v[10:11], 0, v[34:35]
	s_waitcnt lgkmcnt(1)
	v_cvt_pk_bf16_f32 v0, v0, v1
	v_cvt_pk_bf16_f32 v1, v2, v3
	s_waitcnt lgkmcnt(0)
	v_cvt_pk_bf16_f32 v2, v4, v5
	v_cvt_pk_bf16_f32 v3, v6, v7
	v_ashrrev_i32_e32 v4, 4, v16
	v_and_b32_e32 v24, 0x78, v17
	global_store_dwordx4 v[8:9], v[0:3], off nt
	v_ashrrev_i32_e32 v5, 31, v4
	v_lshlrev_b32_e32 v34, 1, v24
	v_and_b32_e32 v0, 0x80, v34
	v_and_b32_e32 v34, 0x70, v34
	v_lshl_or_b32 v34, v0, 6, v34
	v_mul_u32_u24_e32 v0, 0x210, v24
	v_lshlrev_b32_e32 v1, 2, v4
	v_add3_u32 v22, 0, v0, v1
	ds_read2_b32 v[6:7], v22 offset0:64 offset1:80
	ds_read2_b32 v[8:9], v22 offset0:196 offset1:212
	v_add_u32_e32 v23, 0x400, v22
	v_lshlrev_b64 v[4:5], 7, v[4:5]
	ds_read2_b32 v[10:11], v23 offset0:72 offset1:88
	ds_read2_b32 v[12:13], v23 offset0:204 offset1:220
	v_lshl_add_u64 v[4:5], s[8:9], 0, v[4:5]
	s_waitcnt lgkmcnt(2)
	v_cvt_pk_bf16_f32 v0, v6, v8
	v_add_u32_e32 v8, 0x800, v22
	v_add_u32_e32 v6, 0xc00, v22
	ds_read2_b32 v[14:15], v8 offset0:80 offset1:96
	ds_read2_b32 v[16:17], v8 offset0:212 offset1:228
	ds_read2_b32 v[18:19], v6 offset0:88 offset1:104
	ds_read2_b32 v[20:21], v6 offset0:220 offset1:236
	v_lshl_add_u64 v[4:5], v[4:5], 0, s[56:57]
	v_lshl_add_u64 v[4:5], v[4:5], 0, v[34:35]
	s_mov_b32 s8, 0x16180000
	v_add_co_u32_e32 v24, vcc, s8, v4
	s_mov_b32 s8, 0x16180800
	s_nop 0
	v_addc_co_u32_e32 v25, vcc, 0, v5, vcc
	s_waitcnt lgkmcnt(4)
	v_cvt_pk_bf16_f32 v1, v10, v12
	s_waitcnt lgkmcnt(2)
	v_cvt_pk_bf16_f32 v2, v14, v16
	s_waitcnt lgkmcnt(0)
	v_cvt_pk_bf16_f32 v3, v18, v20
	v_add_co_u32_e32 v10, vcc, s8, v4
	global_store_dwordx4 v[24:25], v[0:3], off nt
	s_mov_b32 s8, 0x16181000
	s_nop 0
	v_cvt_pk_bf16_f32 v0, v7, v9
	v_cvt_pk_bf16_f32 v1, v11, v13
	v_cvt_pk_bf16_f32 v2, v15, v17
	v_cvt_pk_bf16_f32 v3, v19, v21
	v_addc_co_u32_e32 v11, vcc, 0, v5, vcc
	global_store_dwordx4 v[10:11], v[0:3], off nt
	ds_read2_b32 v[10:11], v22 offset0:96 offset1:112
	ds_read2_b32 v[12:13], v22 offset0:228 offset1:244
	v_add_u32_e32 v2, 0xa00, v22
	v_add_u32_e32 v3, 0xe00, v22
	ds_read2_b32 v[14:15], v23 offset0:104 offset1:120
	ds_read2_b32 v[16:17], v23 offset0:236 offset1:252
	ds_read2_b32 v[8:9], v8 offset0:112 offset1:128
	ds_read2_b32 v[18:19], v2 offset0:116 offset1:132
	ds_read2_b32 v[6:7], v6 offset0:120 offset1:136
	ds_read2_b32 v[20:21], v3 offset0:124 offset1:140
	v_add_co_u32_e32 v22, vcc, s8, v4
	s_waitcnt lgkmcnt(6)
	v_cvt_pk_bf16_f32 v0, v10, v12
	v_addc_co_u32_e32 v23, vcc, 0, v5, vcc
	s_waitcnt lgkmcnt(4)
	v_cvt_pk_bf16_f32 v1, v14, v16
	s_waitcnt lgkmcnt(2)
	v_cvt_pk_bf16_f32 v2, v8, v18
	s_waitcnt lgkmcnt(0)
	v_cvt_pk_bf16_f32 v3, v6, v20
	v_add_co_u32_e32 v4, vcc, 0x16181800, v4
	global_store_dwordx4 v[22:23], v[0:3], off nt
	s_nop 0
	v_addc_co_u32_e32 v5, vcc, 0, v5, vcc
	v_cvt_pk_bf16_f32 v0, v11, v13
	v_cvt_pk_bf16_f32 v1, v15, v17
	v_cvt_pk_bf16_f32 v2, v9, v19
	v_cvt_pk_bf16_f32 v3, v7, v21
	global_store_dwordx4 v[4:5], v[0:3], off nt

; __global__ void __launch_bounds__(256, 2) mk(Params p_unused, int lo, int hi) {
;     extern __shared__ __attribute__((aligned(16))) char smem[];
	.amdhsa_kernel _Z2mk6Paramsii
		.amdhsa_group_segment_fixed_size 0
		.amdhsa_private_segment_fixed_size 0
		.amdhsa_kernarg_size 496
		.amdhsa_user_sgpr_count 2
		.amdhsa_user_sgpr_dispatch_ptr 0
		.amdhsa_user_sgpr_queue_ptr 0
		.amdhsa_user_sgpr_kernarg_segment_ptr 1
		.amdhsa_user_sgpr_dispatch_id 0
		.amdhsa_user_sgpr_kernarg_preload_length 0
		.amdhsa_user_sgpr_kernarg_preload_offset 0
		.amdhsa_user_sgpr_private_segment_size 0
		.amdhsa_uses_dynamic_stack 0
		.amdhsa_enable_private_segment 0
		.amdhsa_system_sgpr_workgroup_id_x 1
		.amdhsa_system_sgpr_workgroup_id_y 0
		.amdhsa_system_sgpr_workgroup_id_z 0
		.amdhsa_system_sgpr_workgroup_info 0
		.amdhsa_system_vgpr_workitem_id 2
		.amdhsa_next_free_vgpr 248
		.amdhsa_next_free_sgpr 100
		.amdhsa_accum_offset 248
		.amdhsa_reserve_vcc 1
		.amdhsa_float_round_mode_32 0
		.amdhsa_float_round_mode_16_64 0
		.amdhsa_float_denorm_mode_32 3
		.amdhsa_float_denorm_mode_16_64 3
		.amdhsa_dx10_clamp 1
		.amdhsa_ieee_mode 1
		.amdhsa_fp16_overflow 0
		.amdhsa_tg_split 0
		.amdhsa_exception_fp_ieee_invalid_op 0
		.amdhsa_exception_fp_denorm_src 0
		.amdhsa_exception_fp_ieee_div_zero 0
		.amdhsa_exception_fp_ieee_overflow 0
		.amdhsa_exception_fp_ieee_underflow 0
		.amdhsa_exception_fp_ieee_inexact 0
		.amdhsa_exception_int_div_zero 0
	.end_amdhsa_kernel

; __global__ void __launch_bounds__(256, 2) mk(Params p_unused, int lo, int hi) {
;     extern __shared__ __attribute__((aligned(16))) char smem[];
amdhsa.kernels:
  - .agpr_count:     0
    .args:
      - .offset:         0
        .size:           232
        .value_kind:     by_value
      - .offset:         232
        .size:           4
        .value_kind:     by_value
      - .offset:         236
        .size:           4
        .value_kind:     by_value
      - .offset:         240
        .size:           4
        .value_kind:     hidden_block_count_x
      - .offset:         244
        .size:           4
        .value_kind:     hidden_block_count_y
      - .offset:         248
        .size:           4
        .value_kind:     hidden_block_count_z
      - .offset:         252
        .size:           2
        .value_kind:     hidden_group_size_x
      - .offset:         254
        .size:           2
        .value_kind:     hidden_group_size_y
      - .offset:         256
        .size:           2
        .value_kind:     hidden_group_size_z
      - .offset:         258
        .size:           2
        .value_kind:     hidden_remainder_x
      - .offset:         260
        .size:           2
        .value_kind:     hidden_remainder_y
      - .offset:         262
        .size:           2
        .value_kind:     hidden_remainder_z
      - .offset:         280
        .size:           8
        .value_kind:     hidden_global_offset_x
      - .offset:         288
        .size:           8
        .value_kind:     hidden_global_offset_y
      - .offset:         296
        .size:           8
        .value_kind:     hidden_global_offset_z
      - .offset:         304
        .size:           2
        .value_kind:     hidden_grid_dims
      - .offset:         328
        .size:           8
        .value_kind:     hidden_multigrid_sync_arg
      - .offset:         360
        .size:           4
        .value_kind:     hidden_dynamic_lds_size
    .group_segment_fixed_size: 0
    .kernarg_segment_align: 8
    .kernarg_segment_size: 496
    .language:       OpenCL C
    .language_version:
      - 2
      - 0
    .max_flat_workgroup_size: 256
    .name:           _Z2mk6Paramsii
    .private_segment_fixed_size: 0
    .sgpr_count:     106
    .sgpr_spill_count: 128
    .symbol:         _Z2mk6Paramsii.kd
    .uniform_work_group_size: 1
    .uses_dynamic_stack: false
    .vgpr_count:     248
    .vgpr_spill_count: 0
    .wavefront_size: 64
